# adds mod_phase loads hoisted with counted waits; w_up/w_down/w_out prep loads batched
# speedup vs baseline: 1.0216x; 1.0156x over previous
; #define GAS __attribute__((address_space(1)))
; __device__ __forceinline__ unsigned pk2(float lo, float hi) { return cvtpk(lo, hi); }
; template <int ID> __device__ __forceinline__ float wsrc(const GAS float* __restrict__ p0, const GAS float* __restrict__ p1, int n, int k) {
;     ...
;     if (ID == 4) return p0[(size_t)k * 1024 + n];
; template <int ID> __device__ __forceinline__ void prep_mat(const GAS float* __restrict__ p0, const GAS float* __restrict__ p1, GAS bf16_t* __restrict__ dst, int N, int K, int gtid, int NT) {
;     ...
;     for (int it = gtid; it < items; it += NT) {
;         const int nl = it & 7, kl = (it >> 3) & 7, rest = it >> 6, nb = rest % (N / 8), kb = rest / (N / 8), n = nb * 8 + nl, k8 = kb * 8 + kl;
;         u32x4 o;
;         o.x = pk2(wsrc<ID>(p0, p1, n, 8 * k8 + 0), wsrc<ID>(p0, p1, n, 8 * k8 + 1)); o.y = pk2(wsrc<ID>(p0, p1, n, 8 * k8 + 2), wsrc<ID>(p0, p1, n, 8 * k8 + 3));
;         o.z = pk2(wsrc<ID>(p0, p1, n, 8 * k8 + 4), wsrc<ID>(p0, p1, n, 8 * k8 + 5)); o.w = pk2(wsrc<ID>(p0, p1, n, 8 * k8 + 6), wsrc<ID>(p0, p1, n, 8 * k8 + 7));
;         *(GAS u32x4*)(dst + (size_t)n * K + 8 * k8) = o;
.LBB0_278:
	v_ashrrev_i32_e32 v3, 6, v12
	v_lshrrev_b32_e32 v4, 25, v3
	v_add_u32_e32 v4, v3, v4
	v_and_b32_e32 v2, 56, v12
	v_ashrrev_i32_e32 v5, 7, v4
	v_and_b32_e32 v4, 0x1fffff80, v4
	v_sub_u32_e32 v3, v3, v4
	v_lshl_or_b32 v8, v5, 6, v2
	v_lshl_or_b32 v6, v3, 3, v1
	v_ashrrev_i32_e32 v9, 31, v8
	v_ashrrev_i32_e32 v7, 31, v6
	v_lshlrev_b64 v[10:11], 2, v[6:7]
	v_lshlrev_b64 v[28:29], 12, v[8:9]
	v_lshl_add_u64 v[28:29], s[8:9], 0, v[28:29]
	v_lshl_add_u64 v[28:29], v[28:29], 0, v[10:11]
	global_load_dword v20, v[28:29], off
	v_or_b32_e32 v30, 1, v8
	v_ashrrev_i32_e32 v31, 31, v30
	v_lshlrev_b64 v[28:29], 12, v[30:31]
	v_lshl_add_u64 v[28:29], s[8:9], 0, v[28:29]
	v_lshl_add_u64 v[28:29], v[28:29], 0, v[10:11]
	global_load_dword v21, v[28:29], off
	v_or_b32_e32 v30, 2, v8
	v_ashrrev_i32_e32 v31, 31, v30
	v_lshlrev_b64 v[28:29], 12, v[30:31]
	v_lshl_add_u64 v[28:29], s[8:9], 0, v[28:29]
	v_lshl_add_u64 v[28:29], v[28:29], 0, v[10:11]
	global_load_dword v22, v[28:29], off
	v_or_b32_e32 v30, 3, v8
	v_ashrrev_i32_e32 v31, 31, v30
	v_lshlrev_b64 v[28:29], 12, v[30:31]
	v_lshl_add_u64 v[28:29], s[8:9], 0, v[28:29]
	v_lshl_add_u64 v[28:29], v[28:29], 0, v[10:11]
	global_load_dword v23, v[28:29], off
	v_or_b32_e32 v30, 4, v8
	v_ashrrev_i32_e32 v31, 31, v30
	v_lshlrev_b64 v[28:29], 12, v[30:31]
	v_lshl_add_u64 v[28:29], s[8:9], 0, v[28:29]
	v_lshl_add_u64 v[28:29], v[28:29], 0, v[10:11]
	global_load_dword v24, v[28:29], off
	v_or_b32_e32 v30, 5, v8
	v_ashrrev_i32_e32 v31, 31, v30
	v_lshlrev_b64 v[28:29], 12, v[30:31]
	v_lshl_add_u64 v[28:29], s[8:9], 0, v[28:29]
	v_lshl_add_u64 v[28:29], v[28:29], 0, v[10:11]
	global_load_dword v25, v[28:29], off
	v_or_b32_e32 v30, 6, v8
	v_ashrrev_i32_e32 v31, 31, v30
	v_lshlrev_b64 v[28:29], 12, v[30:31]
	v_lshl_add_u64 v[28:29], s[8:9], 0, v[28:29]
	v_lshl_add_u64 v[28:29], v[28:29], 0, v[10:11]
	global_load_dword v26, v[28:29], off
	v_or_b32_e32 v30, 7, v8
	v_ashrrev_i32_e32 v31, 31, v30
	v_lshlrev_b64 v[28:29], 12, v[30:31]
	v_lshl_add_u64 v[28:29], s[8:9], 0, v[28:29]
	v_lshl_add_u64 v[28:29], v[28:29], 0, v[10:11]
	global_load_dword v27, v[28:29], off
	v_lshlrev_b64 v[6:7], 11, v[6:7]
	v_add_u32_e32 v12, s3, v12
	s_mov_b32 s1, 0x1ffff
	v_lshl_add_u64 v[6:7], s[12:13], 0, v[6:7]
	v_cmp_lt_i32_e32 vcc, s1, v12
	v_lshl_add_u64 v[6:7], v[8:9], 1, v[6:7]
	s_or_b64 s[10:11], vcc, s[10:11]
	s_waitcnt vmcnt(0)
	v_cvt_pk_bf16_f32 v2, v20, v21
	v_cvt_pk_bf16_f32 v3, v22, v23
	v_cvt_pk_bf16_f32 v4, v24, v25
	v_cvt_pk_bf16_f32 v5, v26, v27
	global_store_dwordx4 v[6:7], v[2:5], off
	s_andn2_b64 exec, exec, s[10:11]
	s_cbranch_execnz .LBB0_278

; #define GAS __attribute__((address_space(1)))
; __device__ __forceinline__ unsigned pk2(float lo, float hi) { return cvtpk(lo, hi); }
; template <int ID> __device__ __forceinline__ float wsrc(const GAS float* __restrict__ p0, const GAS float* __restrict__ p1, int n, int k) {
;     ...
;     if (ID == 5) return p0[(size_t)k * 5632 + n];
; template <int ID> __device__ __forceinline__ void prep_mat(const GAS float* __restrict__ p0, const GAS float* __restrict__ p1, GAS bf16_t* __restrict__ dst, int N, int K, int gtid, int NT) {
;     ...
;     for (int it = gtid; it < items; it += NT) {
;         const int nl = it & 7, kl = (it >> 3) & 7, rest = it >> 6, nb = rest % (N / 8), kb = rest / (N / 8), n = nb * 8 + nl, k8 = kb * 8 + kl;
;         u32x4 o;
;         o.x = pk2(wsrc<ID>(p0, p1, n, 8 * k8 + 0), wsrc<ID>(p0, p1, n, 8 * k8 + 1)); o.y = pk2(wsrc<ID>(p0, p1, n, 8 * k8 + 2), wsrc<ID>(p0, p1, n, 8 * k8 + 3));
;         o.z = pk2(wsrc<ID>(p0, p1, n, 8 * k8 + 4), wsrc<ID>(p0, p1, n, 8 * k8 + 5)); o.w = pk2(wsrc<ID>(p0, p1, n, 8 * k8 + 6), wsrc<ID>(p0, p1, n, 8 * k8 + 7));
;         *(GAS u32x4*)(dst + (size_t)n * K + 8 * k8) = o;
.LBB0_281:
	v_ashrrev_i32_e32 v3, 6, v6
	v_mul_hi_i32 v4, v3, s60
	v_lshrrev_b32_e32 v5, 31, v4
	v_ashrrev_i32_e32 v4, 7, v4
	v_add_u32_e32 v5, v4, v5
	v_mul_i32_i24_e32 v4, 0x2c0, v5
	v_sub_u32_e32 v3, v3, v4
	v_and_b32_e32 v2, 56, v6
	v_lshl_or_b32 v4, v3, 3, v1
	v_lshl_or_b32 v2, v5, 6, v2
	v_ashrrev_i32_e32 v5, 31, v4
	s_waitcnt lgkmcnt(0)
	v_mov_b64_e32 v[12:13], s[8:9]
	v_lshlrev_b64 v[14:15], 2, v[4:5]
	v_mad_i64_i32 v[28:29], s[12:13], v2, s2, v[12:13]
	v_lshl_add_u64 v[28:29], v[28:29], 0, v[14:15]
	global_load_dword v20, v[28:29], off
	v_or_b32_e32 v30, 1, v2
	v_mad_i64_i32 v[28:29], s[12:13], v30, s2, v[12:13]
	v_lshl_add_u64 v[28:29], v[28:29], 0, v[14:15]
	global_load_dword v21, v[28:29], off
	v_or_b32_e32 v30, 2, v2
	v_mad_i64_i32 v[28:29], s[12:13], v30, s2, v[12:13]
	v_lshl_add_u64 v[28:29], v[28:29], 0, v[14:15]
	global_load_dword v22, v[28:29], off
	v_or_b32_e32 v30, 3, v2
	v_mad_i64_i32 v[28:29], s[12:13], v30, s2, v[12:13]
	v_lshl_add_u64 v[28:29], v[28:29], 0, v[14:15]
	global_load_dword v23, v[28:29], off
	v_or_b32_e32 v30, 4, v2
	v_mad_i64_i32 v[28:29], s[12:13], v30, s2, v[12:13]
	v_lshl_add_u64 v[28:29], v[28:29], 0, v[14:15]
	global_load_dword v24, v[28:29], off
	v_or_b32_e32 v30, 5, v2
	v_mad_i64_i32 v[28:29], s[12:13], v30, s2, v[12:13]
	v_lshl_add_u64 v[28:29], v[28:29], 0, v[14:15]
	global_load_dword v25, v[28:29], off
	v_or_b32_e32 v30, 6, v2
	v_mad_i64_i32 v[28:29], s[12:13], v30, s2, v[12:13]
	v_lshl_add_u64 v[28:29], v[28:29], 0, v[14:15]
	global_load_dword v26, v[28:29], off
	v_or_b32_e32 v30, 7, v2
	v_mad_i64_i32 v[28:29], s[12:13], v30, s2, v[12:13]
	v_lshl_add_u64 v[28:29], v[28:29], 0, v[14:15]
	global_load_dword v27, v[28:29], off
	v_lshlrev_b64 v[4:5], 11, v[4:5]
	v_add_u32_e32 v6, s3, v6
	s_mov_b32 s1, 0xaffff
	v_ashrrev_i32_e32 v3, 31, v2
	v_lshl_add_u64 v[4:5], s[22:23], 0, v[4:5]
	v_cmp_lt_i32_e32 vcc, s1, v6
	s_or_b64 s[10:11], vcc, s[10:11]
	v_lshl_add_u64 v[2:3], v[2:3], 1, v[4:5]
	s_waitcnt vmcnt(0)
	v_cvt_pk_bf16_f32 v8, v20, v21
	v_cvt_pk_bf16_f32 v9, v22, v23
	v_cvt_pk_bf16_f32 v10, v24, v25
	v_cvt_pk_bf16_f32 v11, v26, v27
	global_store_dwordx4 v[2:3], v[8:11], off
	s_andn2_b64 exec, exec, s[10:11]
	s_cbranch_execnz .LBB0_281

; #define GAS __attribute__((address_space(1)))
; __device__ __forceinline__ unsigned pk2(float lo, float hi) { return cvtpk(lo, hi); }
; template <int ID> __device__ __forceinline__ float wsrc(const GAS float* __restrict__ p0, const GAS float* __restrict__ p1, int n, int k) {
;     ...
;     return p0[(size_t)k * 1024 + n];
; template <int ID> __device__ __forceinline__ void prep_mat(const GAS float* __restrict__ p0, const GAS float* __restrict__ p1, GAS bf16_t* __restrict__ dst, int N, int K, int gtid, int NT) {
;     ...
;     for (int it = gtid; it < items; it += NT) {
;         const int nl = it & 7, kl = (it >> 3) & 7, rest = it >> 6, nb = rest % (N / 8), kb = rest / (N / 8), n = nb * 8 + nl, k8 = kb * 8 + kl;
;         u32x4 o;
;         o.x = pk2(wsrc<ID>(p0, p1, n, 8 * k8 + 0), wsrc<ID>(p0, p1, n, 8 * k8 + 1)); o.y = pk2(wsrc<ID>(p0, p1, n, 8 * k8 + 2), wsrc<ID>(p0, p1, n, 8 * k8 + 3));
;         o.z = pk2(wsrc<ID>(p0, p1, n, 8 * k8 + 4), wsrc<ID>(p0, p1, n, 8 * k8 + 5)); o.w = pk2(wsrc<ID>(p0, p1, n, 8 * k8 + 6), wsrc<ID>(p0, p1, n, 8 * k8 + 7));
;         *(GAS u32x4*)(dst + (size_t)n * K + 8 * k8) = o;
.LBB0_284:
	v_ashrrev_i32_e32 v3, 6, v12
	v_lshrrev_b32_e32 v4, 25, v3
	v_add_u32_e32 v4, v3, v4
	v_and_b32_e32 v2, 56, v12
	v_ashrrev_i32_e32 v5, 7, v4
	v_and_b32_e32 v4, 0x1fffff80, v4
	v_sub_u32_e32 v3, v3, v4
	v_lshl_or_b32 v8, v5, 6, v2
	v_lshl_or_b32 v6, v3, 3, v1
	v_ashrrev_i32_e32 v9, 31, v8
	v_ashrrev_i32_e32 v7, 31, v6
	v_lshlrev_b64 v[10:11], 2, v[6:7]
	v_lshlrev_b64 v[28:29], 12, v[8:9]
	v_lshl_add_u64 v[28:29], s[8:9], 0, v[28:29]
	v_lshl_add_u64 v[28:29], v[28:29], 0, v[10:11]
	global_load_dword v20, v[28:29], off
	v_or_b32_e32 v30, 1, v8
	v_ashrrev_i32_e32 v31, 31, v30
	v_lshlrev_b64 v[28:29], 12, v[30:31]
	v_lshl_add_u64 v[28:29], s[8:9], 0, v[28:29]
	v_lshl_add_u64 v[28:29], v[28:29], 0, v[10:11]
	global_load_dword v21, v[28:29], off
	v_or_b32_e32 v30, 2, v8
	v_ashrrev_i32_e32 v31, 31, v30
	v_lshlrev_b64 v[28:29], 12, v[30:31]
	v_lshl_add_u64 v[28:29], s[8:9], 0, v[28:29]
	v_lshl_add_u64 v[28:29], v[28:29], 0, v[10:11]
	global_load_dword v22, v[28:29], off
	v_or_b32_e32 v30, 3, v8
	v_ashrrev_i32_e32 v31, 31, v30
	v_lshlrev_b64 v[28:29], 12, v[30:31]
	v_lshl_add_u64 v[28:29], s[8:9], 0, v[28:29]
	v_lshl_add_u64 v[28:29], v[28:29], 0, v[10:11]
	global_load_dword v23, v[28:29], off
	v_or_b32_e32 v30, 4, v8
	v_ashrrev_i32_e32 v31, 31, v30
	v_lshlrev_b64 v[28:29], 12, v[30:31]
	v_lshl_add_u64 v[28:29], s[8:9], 0, v[28:29]
	v_lshl_add_u64 v[28:29], v[28:29], 0, v[10:11]
	global_load_dword v24, v[28:29], off
	v_or_b32_e32 v30, 5, v8
	v_ashrrev_i32_e32 v31, 31, v30
	v_lshlrev_b64 v[28:29], 12, v[30:31]
	v_lshl_add_u64 v[28:29], s[8:9], 0, v[28:29]
	v_lshl_add_u64 v[28:29], v[28:29], 0, v[10:11]
	global_load_dword v25, v[28:29], off
	v_or_b32_e32 v30, 6, v8
	v_ashrrev_i32_e32 v31, 31, v30
	v_lshlrev_b64 v[28:29], 12, v[30:31]
	v_lshl_add_u64 v[28:29], s[8:9], 0, v[28:29]
	v_lshl_add_u64 v[28:29], v[28:29], 0, v[10:11]
	global_load_dword v26, v[28:29], off
	v_or_b32_e32 v30, 7, v8
	v_ashrrev_i32_e32 v31, 31, v30
	v_lshlrev_b64 v[28:29], 12, v[30:31]
	v_lshl_add_u64 v[28:29], s[8:9], 0, v[28:29]
	v_lshl_add_u64 v[28:29], v[28:29], 0, v[10:11]
	global_load_dword v27, v[28:29], off
	s_movk_i32 s1, 0xb00
	v_mul_lo_u32 v6, v6, s1
	v_add_u32_e32 v12, s3, v12
	v_cmp_lt_i32_e32 vcc, s99, v12
	s_or_b64 s[10:11], vcc, s[10:11]
	v_ashrrev_i32_e32 v7, 31, v6
	v_lshl_add_u64 v[6:7], v[6:7], 1, s[42:43]
	v_lshl_add_u64 v[6:7], v[8:9], 1, v[6:7]
	s_waitcnt vmcnt(0)
	v_cvt_pk_bf16_f32 v2, v20, v21
	v_cvt_pk_bf16_f32 v3, v22, v23
	v_cvt_pk_bf16_f32 v4, v24, v25
	v_cvt_pk_bf16_f32 v5, v26, v27
	global_store_dwordx4 v[6:7], v[2:5], off
	s_andn2_b64 exec, exec, s[10:11]
	s_cbranch_execnz .LBB0_284

; __device__ __forceinline__ void mod_phase(const GAS float* __restrict__ cvec, const GAS float* __restrict__ cctx, const GAS float* __restrict__ wmod, const GAS float* __restrict__ bmod, GAS float* __restrict__ mod, LAS float* scr, int gw, int NGW, int lane) {
;     ...
; #pragma unroll 8
;         for (int kk = 0; kk < 64; ++kk) { const float w = wmod[(size_t)(k0 + kk) * NMOD + n];
; #pragma unroll
;             for (int r = 0; r < 9; ++r) acc[r] += scr[r * 64 + kk] * w; }
;         const float bias = kc == 0 ? bmod[n] : 0.f;
; #pragma unroll
;         for (int r = 0; r < 9; ++r) atomicAdd((float*)(mod + r * NMOD + n), acc[r] + bias);
.LBB0_301:
	v_lshl_add_u64 v[48:49], v[4:5], 0, s[22:23]
	global_load_dword v60, v[48:49], off
	v_add_co_u32_e32 v76, vcc, s46, v48
	s_nop 1
	v_addc_co_u32_e32 v77, vcc, 0, v49, vcc
	global_load_dword v62, v[76:77], off
	v_add_co_u32_e32 v78, vcc, s46, v76
	s_nop 1
	v_addc_co_u32_e32 v79, vcc, 0, v77, vcc
	global_load_dword v64, v[78:79], off
	v_add_co_u32_e32 v76, vcc, s46, v78
	s_nop 1
	v_addc_co_u32_e32 v77, vcc, 0, v79, vcc
	global_load_dword v66, v[76:77], off
	v_add_co_u32_e32 v78, vcc, s46, v76
	s_nop 1
	v_addc_co_u32_e32 v79, vcc, 0, v77, vcc
	global_load_dword v68, v[78:79], off
	v_add_co_u32_e32 v76, vcc, s46, v78
	s_nop 1
	v_addc_co_u32_e32 v77, vcc, 0, v79, vcc
	global_load_dword v70, v[76:77], off
	v_add_co_u32_e32 v78, vcc, s46, v76
	s_nop 1
	v_addc_co_u32_e32 v79, vcc, 0, v77, vcc
	global_load_dword v72, v[78:79], off
	v_add_co_u32_e32 v76, vcc, s46, v78
	s_nop 1
	v_addc_co_u32_e32 v77, vcc, 0, v79, vcc
	global_load_dword v74, v[76:77], off
	v_mov_b32_e32 v15, s0
	ds_read_b128 v[16:19], v15
	ds_read_b128 v[20:23], v15 offset:16
	ds_read_b128 v[24:27], v15 offset:256
	s_mov_b32 s1, 0x24000
	s_add_u32 s22, s22, 0x30000
	s_waitcnt lgkmcnt(2)
	v_mov_b32_e32 v28, v16
	s_addc_u32 s23, s23, 0
	s_waitcnt lgkmcnt(0)
	v_mov_b32_e32 v29, v24
	v_mov_b32_e32 v24, v17
	s_add_i32 s0, s0, 32
	s_cmp_eq_u32 s22, 0x180000
	s_waitcnt vmcnt(7)
	v_pk_fma_f32 v[52:53], v[60:61], v[28:29], v[12:13] op_sel_hi:[0,1,1]
	ds_read_b128 v[28:31], v15 offset:512
	ds_read_b128 v[32:35], v15 offset:768
	s_waitcnt lgkmcnt(1)
	v_mov_b32_e32 v12, v28
	s_waitcnt lgkmcnt(0)
	v_mov_b32_e32 v13, v32
	v_pk_fma_f32 v[54:55], v[60:61], v[12:13], v[10:11] op_sel_hi:[0,1,1]
	ds_read_b128 v[10:13], v15 offset:1024
	ds_read_b128 v[36:39], v15 offset:1280
	v_mov_b32_e32 v32, v29
	s_waitcnt lgkmcnt(1)
	v_mov_b32_e32 v40, v10
	s_waitcnt lgkmcnt(0)
	v_mov_b32_e32 v41, v36
	v_pk_fma_f32 v[56:57], v[60:61], v[40:41], v[8:9] op_sel_hi:[0,1,1]
	ds_read_b128 v[40:43], v15 offset:1536
	ds_read_b128 v[44:47], v15 offset:1792
	v_mov_b32_e32 v36, v11
	s_waitcnt lgkmcnt(1)
	v_mov_b32_e32 v8, v40
	s_waitcnt lgkmcnt(0)
	v_mov_b32_e32 v9, v44
	v_pk_fma_f32 v[58:59], v[60:61], v[8:9], v[6:7] op_sel_hi:[0,1,1]
	ds_read_b128 v[6:9], v15 offset:2048
	v_mov_b32_e32 v44, v41
	s_waitcnt lgkmcnt(0)
	v_fmac_f32_e32 v14, v60, v6
	s_waitcnt vmcnt(6)
	v_pk_fma_f32 v[16:17], v[62:63], v[24:25], v[52:53] op_sel_hi:[0,1,1]
	v_pk_fma_f32 v[24:25], v[62:63], v[32:33], v[54:55] op_sel_hi:[0,1,1]
	v_pk_fma_f32 v[10:11], v[62:63], v[36:37], v[56:57] op_sel_hi:[0,1,1]
	v_pk_fma_f32 v[28:29], v[62:63], v[44:45], v[58:59] op_sel_hi:[0,1,1]
	v_fmac_f32_e32 v14, v62, v7
	v_mov_b32_e32 v32, v18
	v_mov_b32_e32 v33, v26
	v_mov_b32_e32 v26, v19
	v_mov_b32_e32 v18, v20
	s_waitcnt vmcnt(5)
	v_pk_fma_f32 v[16:17], v[64:65], v[32:33], v[16:17] op_sel_hi:[0,1,1]
	v_mov_b32_e32 v32, v30
	v_mov_b32_e32 v33, v34
	v_pk_fma_f32 v[24:25], v[64:65], v[32:33], v[24:25] op_sel_hi:[0,1,1]
	v_mov_b32_e32 v32, v12
	v_mov_b32_e32 v33, v38
	v_pk_fma_f32 v[10:11], v[64:65], v[32:33], v[10:11] op_sel_hi:[0,1,1]
	v_mov_b32_e32 v32, v42
	v_mov_b32_e32 v33, v46
	v_pk_fma_f32 v[28:29], v[64:65], v[32:33], v[28:29] op_sel_hi:[0,1,1]
	v_fmac_f32_e32 v14, v64, v8
	v_mov_b32_e32 v34, v31
	v_mov_b32_e32 v38, v13
	v_mov_b32_e32 v46, v43
	s_waitcnt vmcnt(4)
	v_pk_fma_f32 v[16:17], v[66:67], v[26:27], v[16:17] op_sel_hi:[0,1,1]
	v_pk_fma_f32 v[30:31], v[66:67], v[34:35], v[24:25] op_sel_hi:[0,1,1]
	v_pk_fma_f32 v[10:11], v[66:67], v[38:39], v[10:11] op_sel_hi:[0,1,1]
	v_pk_fma_f32 v[12:13], v[66:67], v[46:47], v[28:29] op_sel_hi:[0,1,1]
	v_fmac_f32_e32 v14, v66, v9
	ds_read_b128 v[6:9], v15 offset:272
	s_waitcnt lgkmcnt(0)
	v_mov_b32_e32 v19, v6
	v_mov_b32_e32 v6, v21
	s_waitcnt vmcnt(3)
	v_pk_fma_f32 v[52:53], v[68:69], v[18:19], v[16:17] op_sel_hi:[0,1,1]
	ds_read_b128 v[16:19], v15 offset:528
	ds_read_b128 v[24:27], v15 offset:784
	s_waitcnt lgkmcnt(1)
	v_mov_b32_e32 v28, v16
	s_waitcnt lgkmcnt(0)
	v_mov_b32_e32 v29, v24
	v_pk_fma_f32 v[54:55], v[68:69], v[28:29], v[30:31] op_sel_hi:[0,1,1]
	ds_read_b128 v[28:31], v15 offset:1040
	ds_read_b128 v[32:35], v15 offset:1296
	v_mov_b32_e32 v24, v17
	s_waitcnt lgkmcnt(1)
	v_mov_b32_e32 v36, v28
	s_waitcnt lgkmcnt(0)
	v_mov_b32_e32 v37, v32
	v_pk_fma_f32 v[10:11], v[68:69], v[36:37], v[10:11] op_sel_hi:[0,1,1]
	ds_read_b128 v[36:39], v15 offset:1552
	ds_read_b128 v[40:43], v15 offset:1808
	v_mov_b32_e32 v32, v29
	s_waitcnt lgkmcnt(1)
	v_mov_b32_e32 v44, v36
	s_waitcnt lgkmcnt(0)
	v_mov_b32_e32 v45, v40
	v_pk_fma_f32 v[12:13], v[68:69], v[44:45], v[12:13] op_sel_hi:[0,1,1]
	ds_read_b128 v[44:47], v15 offset:2064
	v_mov_b32_e32 v40, v37
	s_waitcnt lgkmcnt(0)
	v_fmac_f32_e32 v14, v68, v44
	s_waitcnt vmcnt(2)
	v_pk_fma_f32 v[6:7], v[70:71], v[6:7], v[52:53] op_sel_hi:[0,1,1]
	v_pk_fma_f32 v[20:21], v[70:71], v[24:25], v[54:55] op_sel_hi:[0,1,1]
	v_pk_fma_f32 v[10:11], v[70:71], v[32:33], v[10:11] op_sel_hi:[0,1,1]
	v_pk_fma_f32 v[12:13], v[70:71], v[40:41], v[12:13] op_sel_hi:[0,1,1]
	v_fmac_f32_e32 v14, v70, v45
	v_mov_b32_e32 v24, v22
	v_mov_b32_e32 v25, v8
	s_mov_b32 s1, 0x2a000
	v_mov_b32_e32 v8, v23
	s_waitcnt vmcnt(1)
	v_pk_fma_f32 v[6:7], v[72:73], v[24:25], v[6:7] op_sel_hi:[0,1,1]
	v_mov_b32_e32 v24, v18
	v_mov_b32_e32 v25, v26
	v_pk_fma_f32 v[20:21], v[72:73], v[24:25], v[20:21] op_sel_hi:[0,1,1]
	v_mov_b32_e32 v24, v30
	v_mov_b32_e32 v25, v34
	v_pk_fma_f32 v[24:25], v[72:73], v[24:25], v[10:11] op_sel_hi:[0,1,1]
	v_mov_b32_e32 v10, v38
	v_mov_b32_e32 v11, v42
	v_pk_fma_f32 v[28:29], v[72:73], v[10:11], v[12:13] op_sel_hi:[0,1,1]
	v_fmac_f32_e32 v14, v72, v46
	v_mov_b32_e32 v26, v19
	v_mov_b32_e32 v34, v31
	v_mov_b32_e32 v42, v39
	s_waitcnt vmcnt(0)
	v_pk_fma_f32 v[12:13], v[74:75], v[8:9], v[6:7] op_sel_hi:[0,1,1]
	v_pk_fma_f32 v[10:11], v[74:75], v[26:27], v[20:21] op_sel_hi:[0,1,1]
	v_pk_fma_f32 v[8:9], v[74:75], v[34:35], v[24:25] op_sel_hi:[0,1,1]
	v_pk_fma_f32 v[6:7], v[74:75], v[42:43], v[28:29] op_sel_hi:[0,1,1]
	v_fmac_f32_e32 v14, v74, v47
	s_cbranch_scc0 .LBB0_301
	s_add_i32 s0, s16, 0x5f
	s_mov_b32 s1, 0x12000
	s_cmpk_lt_u32 s0, 0xbf
	v_mov_b32_e32 v4, 0
	s_cbranch_scc0 .LBB0_299
	v_lshl_add_u64 v[4:5], v[2:3], 2, s[12:13]
	global_load_dword v4, v[4:5], off
	s_branch .LBB0_299
